# prep: conditioning-vector staging (17 loads) and Fourier-fold weight staging (16 loads) issued together
# speedup vs baseline: 1.0685x; 1.0041x over previous
.Lcvt_join:
	s_mov_b64 exec, s[18:19]
	s_mov_b64 s[4:5], exec
	s_waitcnt vmcnt(0)
	ds_write_b32 v4, v21
	ds_write_b32 v5, v22
	ds_write_b32 v7, v23
	ds_write_b32 v9, v24
	ds_write_b32 v11, v25
	ds_write_b32 v13, v26
	ds_write_b32 v15, v27
	s_branch .LBB0_438
	s_nop 0
	s_nop 0
	s_nop 0
	s_nop 0
	s_nop 0
	s_nop 0
	s_nop 0
	s_nop 0
	s_nop 0
	s_nop 0
	s_nop 0
	s_nop 0

.LBB0_495:
	v_ashrrev_i32_e32 v12, 7, v6
	v_add_u32_e32 v8, s29, v12
	v_mad_i64_i32 v[8:9], s[12:13], v8, s57, v[4:5]
	s_mov_b64 s[98:99], 0x8100
	v_mad_u64_u32 v[10:11], s[12:13], v12, s60, v[0:1]
	global_load_dword v80, v[8:9], off
	v_lshl_add_u64 v[8:9], v[8:9], 0, s[98:99]
	global_load_dword v81, v[8:9], off
	v_lshl_add_u64 v[8:9], v[8:9], 0, s[98:99]
	global_load_dword v82, v[8:9], off
	v_lshl_add_u64 v[8:9], v[8:9], 0, s[98:99]
	global_load_dword v83, v[8:9], off
	v_lshl_add_u64 v[8:9], v[8:9], 0, s[98:99]
	global_load_dword v84, v[8:9], off
	v_lshl_add_u64 v[8:9], v[8:9], 0, s[98:99]
	global_load_dword v85, v[8:9], off
	v_lshl_add_u64 v[8:9], v[8:9], 0, s[98:99]
	global_load_dword v86, v[8:9], off
	v_lshl_add_u64 v[8:9], v[8:9], 0, s[98:99]
	global_load_dword v87, v[8:9], off
	v_lshl_add_u64 v[8:9], v[8:9], 0, s[98:99]
	global_load_dword v88, v[8:9], off
	v_lshl_add_u64 v[8:9], v[8:9], 0, s[98:99]
	global_load_dword v89, v[8:9], off
	v_lshl_add_u64 v[8:9], v[8:9], 0, s[98:99]
	global_load_dword v90, v[8:9], off
	v_lshl_add_u64 v[8:9], v[8:9], 0, s[98:99]
	global_load_dword v91, v[8:9], off
	v_lshl_add_u64 v[8:9], v[8:9], 0, s[98:99]
	global_load_dword v92, v[8:9], off
	v_lshl_add_u64 v[8:9], v[8:9], 0, s[98:99]
	global_load_dword v93, v[8:9], off
	v_lshl_add_u64 v[8:9], v[8:9], 0, s[98:99]
	global_load_dword v94, v[8:9], off
	v_lshl_add_u64 v[8:9], v[8:9], 0, s[98:99]
	global_load_dword v95, v[8:9], off
	s_waitcnt vmcnt(0)
	ds_write_b32 v10, v80
	ds_write_b32 v10, v81 offset:2064
	ds_write_b32 v10, v82 offset:4128
	ds_write_b32 v10, v83 offset:6192
	ds_write_b32 v10, v84 offset:8256
	ds_write_b32 v10, v85 offset:10320
	ds_write_b32 v10, v86 offset:12384
	ds_write_b32 v10, v87 offset:14448
	ds_write_b32 v10, v88 offset:16512
	ds_write_b32 v10, v89 offset:18576
	ds_write_b32 v10, v90 offset:20640
	ds_write_b32 v10, v91 offset:22704
	ds_write_b32 v10, v92 offset:24768
	ds_write_b32 v10, v93 offset:26832
	ds_write_b32 v10, v94 offset:28896
	ds_write_b32 v10, v95 offset:30960
	v_mov_b32_e32 v3, 0
	s_mov_b64 s[24:25], exec
	s_or_b64 exec, exec, s[24:25]
	s_orn2_b64 s[12:13], s[10:11], exec
	v_mov_b32_e32 v3, v42

.LBB0_551:
	s_and_b32 s18, s23, 3
	s_barrier
	s_and_saveexec_b64 s[2:3], vcc
	s_cbranch_execz .LBB0_558
	v_lshl_or_b32 v10, s18, 8, v5
	s_load_dwordx2 s[14:15], s[0:1], 0x8
	s_load_dwordx2 s[12:13], s[0:1], 0x18
	v_ashrrev_i32_e32 v15, 8, v176
	v_lshl_or_b32 v12, v15, 10, v10
	v_ashrrev_i32_e32 v13, 31, v12
	s_mov_b64 s[10:11], 0x2000
	s_waitcnt lgkmcnt(0)
	v_lshl_add_u64 v[12:13], v[12:13], 2, s[14:15]
	global_load_dword v56, v[12:13], off
	v_lshl_add_u64 v[12:13], v[12:13], 0, s[10:11]
	global_load_dword v57, v[12:13], off
	v_lshl_add_u64 v[12:13], v[12:13], 0, s[10:11]
	global_load_dword v58, v[12:13], off
	v_lshl_add_u64 v[12:13], v[12:13], 0, s[10:11]
	global_load_dword v59, v[12:13], off
	v_lshl_add_u64 v[12:13], v[12:13], 0, s[10:11]
	global_load_dword v60, v[12:13], off
	v_lshl_add_u64 v[12:13], v[12:13], 0, s[10:11]
	global_load_dword v61, v[12:13], off
	v_lshl_add_u64 v[12:13], v[12:13], 0, s[10:11]
	global_load_dword v62, v[12:13], off
	v_lshl_add_u64 v[12:13], v[12:13], 0, s[10:11]
	global_load_dword v63, v[12:13], off
	v_lshl_add_u64 v[12:13], v[12:13], 0, s[10:11]
	global_load_dword v64, v[12:13], off
	v_lshl_add_u64 v[12:13], v[12:13], 0, s[10:11]
	global_load_dword v65, v[12:13], off
	v_lshl_add_u64 v[12:13], v[12:13], 0, s[10:11]
	global_load_dword v66, v[12:13], off
	v_lshl_add_u64 v[12:13], v[12:13], 0, s[10:11]
	global_load_dword v67, v[12:13], off
	v_lshl_add_u64 v[12:13], v[12:13], 0, s[10:11]
	global_load_dword v68, v[12:13], off
	v_lshl_add_u64 v[12:13], v[12:13], 0, s[10:11]
	global_load_dword v69, v[12:13], off
	v_lshl_add_u64 v[12:13], v[12:13], 0, s[10:11]
	global_load_dword v70, v[12:13], off
	v_lshl_add_u64 v[12:13], v[12:13], 0, s[10:11]
	global_load_dword v71, v[12:13], off
	s_movk_i32 s10, 0x100
	v_cmp_gt_u32_e64 s[10:11], s10, v176
	s_and_saveexec_b64 s[14:15], s[10:11]
	v_lshlrev_b32_e32 v192, 2, v10
	v_lshl_add_u64 v[12:13], s[12:13], 0, v[192:193]
	global_load_dword v72, v[12:13], off
	s_or_b64 exec, exec, s[14:15]
	s_waitcnt vmcnt(0)
	v_mul_f32_e32 v13, 0xbfb8aa3b, v56
	v_exp_f32_e32 v13, v13
	s_nop 0
	v_add_f32_e32 v13, 1.0, v13
	v_rcp_f32_e32 v13, v13
	s_nop 0
	v_mul_f32_e32 v12, v56, v13
	ds_write_b32 v52, v12
	v_mul_f32_e32 v13, 0xbfb8aa3b, v57
	v_exp_f32_e32 v13, v13
	s_nop 0
	v_add_f32_e32 v13, 1.0, v13
	v_rcp_f32_e32 v13, v13
	s_nop 0
	v_mul_f32_e32 v12, v57, v13
	ds_write_b32 v52, v12 offset:2048
	v_mul_f32_e32 v13, 0xbfb8aa3b, v58
	v_exp_f32_e32 v13, v13
	s_nop 0
	v_add_f32_e32 v13, 1.0, v13
	v_rcp_f32_e32 v13, v13
	s_nop 0
	v_mul_f32_e32 v12, v58, v13
	ds_write_b32 v52, v12 offset:4096
	v_mul_f32_e32 v13, 0xbfb8aa3b, v59
	v_exp_f32_e32 v13, v13
	s_nop 0
	v_add_f32_e32 v13, 1.0, v13
	v_rcp_f32_e32 v13, v13
	s_nop 0
	v_mul_f32_e32 v12, v59, v13
	ds_write_b32 v52, v12 offset:6144
	v_mul_f32_e32 v13, 0xbfb8aa3b, v60
	v_exp_f32_e32 v13, v13
	s_nop 0
	v_add_f32_e32 v13, 1.0, v13
	v_rcp_f32_e32 v13, v13
	s_nop 0
	v_mul_f32_e32 v12, v60, v13
	ds_write_b32 v52, v12 offset:8192
	v_mul_f32_e32 v13, 0xbfb8aa3b, v61
	v_exp_f32_e32 v13, v13
	s_nop 0
	v_add_f32_e32 v13, 1.0, v13
	v_rcp_f32_e32 v13, v13
	s_nop 0
	v_mul_f32_e32 v12, v61, v13
	ds_write_b32 v52, v12 offset:10240
	v_mul_f32_e32 v13, 0xbfb8aa3b, v62
	v_exp_f32_e32 v13, v13
	s_nop 0
	v_add_f32_e32 v13, 1.0, v13
	v_rcp_f32_e32 v13, v13
	s_nop 0
	v_mul_f32_e32 v12, v62, v13
	ds_write_b32 v52, v12 offset:12288
	v_mul_f32_e32 v13, 0xbfb8aa3b, v63
	v_exp_f32_e32 v13, v13
	s_nop 0
	v_add_f32_e32 v13, 1.0, v13
	v_rcp_f32_e32 v13, v13
	s_nop 0
	v_mul_f32_e32 v12, v63, v13
	ds_write_b32 v52, v12 offset:14336
	v_mul_f32_e32 v13, 0xbfb8aa3b, v64
	v_exp_f32_e32 v13, v13
	s_nop 0
	v_add_f32_e32 v13, 1.0, v13
	v_rcp_f32_e32 v13, v13
	s_nop 0
	v_mul_f32_e32 v12, v64, v13
	ds_write_b32 v52, v12 offset:16384
	v_mul_f32_e32 v13, 0xbfb8aa3b, v65
	v_exp_f32_e32 v13, v13
	s_nop 0
	v_add_f32_e32 v13, 1.0, v13
	v_rcp_f32_e32 v13, v13
	s_nop 0
	v_mul_f32_e32 v12, v65, v13
	ds_write_b32 v52, v12 offset:18432
	v_mul_f32_e32 v13, 0xbfb8aa3b, v66
	v_exp_f32_e32 v13, v13
	s_nop 0
	v_add_f32_e32 v13, 1.0, v13
	v_rcp_f32_e32 v13, v13
	s_nop 0
	v_mul_f32_e32 v12, v66, v13
	ds_write_b32 v52, v12 offset:20480
	v_mul_f32_e32 v13, 0xbfb8aa3b, v67
	v_exp_f32_e32 v13, v13
	s_nop 0
	v_add_f32_e32 v13, 1.0, v13
	v_rcp_f32_e32 v13, v13
	s_nop 0
	v_mul_f32_e32 v12, v67, v13
	ds_write_b32 v52, v12 offset:22528
	v_mul_f32_e32 v13, 0xbfb8aa3b, v68
	v_exp_f32_e32 v13, v13
	s_nop 0
	v_add_f32_e32 v13, 1.0, v13
	v_rcp_f32_e32 v13, v13
	s_nop 0
	v_mul_f32_e32 v12, v68, v13
	ds_write_b32 v52, v12 offset:24576
	v_mul_f32_e32 v13, 0xbfb8aa3b, v69
	v_exp_f32_e32 v13, v13
	s_nop 0
	v_add_f32_e32 v13, 1.0, v13
	v_rcp_f32_e32 v13, v13
	s_nop 0
	v_mul_f32_e32 v12, v69, v13
	ds_write_b32 v52, v12 offset:26624
	v_mul_f32_e32 v13, 0xbfb8aa3b, v70
	v_exp_f32_e32 v13, v13
	s_nop 0
	v_add_f32_e32 v13, 1.0, v13
	v_rcp_f32_e32 v13, v13
	s_nop 0
	v_mul_f32_e32 v12, v70, v13
	ds_write_b32 v52, v12 offset:28672
	v_mul_f32_e32 v13, 0xbfb8aa3b, v71
	v_exp_f32_e32 v13, v13
	s_nop 0
	v_add_f32_e32 v13, 1.0, v13
	v_rcp_f32_e32 v13, v13
	s_nop 0
	v_mul_f32_e32 v12, v71, v13
	ds_write_b32 v52, v12 offset:30720
	s_and_saveexec_b64 s[14:15], s[10:11]
	v_mul_f32_e32 v13, 0xbfb8aa3b, v72
	v_exp_f32_e32 v13, v13
	s_nop 0
	v_add_f32_e32 v13, 1.0, v13
	v_rcp_f32_e32 v13, v13
	s_nop 0
	v_mul_f32_e32 v12, v72, v13
	ds_write_b32 v52, v12 offset:32768
	s_or_b64 exec, exec, s[14:15]
